# spatial gating W_s staging: 7 of 8 loads issued together with counted waits, on top of the hazard-clean cvt_pk/seam/prologue stack
# baseline (speedup 1.0000x reference)
.LBB0_761:
	s_and_b32 s0, s96, 15
	s_cmp_eq_u32 s0, s92
	s_cbranch_scc1 .LBB0_763
	s_lshl_b32 s80, s0, 16
	v_lshl_add_u64 v[0:1], v[60:61], 0, s[80:81]
	v_mov_b32_e32 v65, v59
	v_lshl_add_u64 v[2:3], v[0:1], 0, v[64:65]
	global_load_dwordx4 v[2:5], v[2:3], off
	v_mov_b32_e32 v6, s81
	v_mov_b32_e32 v67, v59
	v_mov_b32_e32 v69, v59
	v_mov_b32_e32 v71, v59
	v_mov_b32_e32 v73, v59
	v_mov_b32_e32 v75, v59
	v_mov_b32_e32 v77, v59
	v_mov_b32_e32 v79, v59
	s_lshl_b32 s1, s0, 7
	v_add_lshl_u32 v16, s1, v57, 2
	s_mov_b32 s92, s0
	v_lshl_add_u64 v[226:227], v[0:1], 0, v[66:67]
	global_load_dwordx4 v[226:229], v[226:227], off
	v_lshl_add_u64 v[230:231], v[0:1], 0, v[68:69]
	global_load_dwordx4 v[230:233], v[230:231], off
	v_lshl_add_u64 v[234:235], v[0:1], 0, v[70:71]
	global_load_dwordx4 v[234:237], v[234:235], off
	v_lshl_add_u64 v[238:239], v[0:1], 0, v[72:73]
	global_load_dwordx4 v[238:241], v[238:239], off
	v_lshl_add_u64 v[242:243], v[0:1], 0, v[74:75]
	global_load_dwordx4 v[242:245], v[242:243], off
	v_lshl_add_u64 v[246:247], v[0:1], 0, v[76:77]
	global_load_dwordx4 v[246:249], v[246:247], off
	v_lshl_add_u64 v[0:1], v[0:1], 0, v[78:79]
	s_waitcnt vmcnt(6)
	v_cndmask_b32_e64 v6, v2, v6, s[6:7]
	v_cndmask_b32_e64 v2, v6, v2, s[8:9]
	v_cndmask_b32_e64 v3, 0, v3, s[8:9]
	v_cndmask_b32_e64 v4, v4, 0, s[10:11]
	v_cndmask_b32_e64 v5, v5, 0, s[12:13]
	v_cvt_pk_bf16_f32 v2, v2, v3
	v_cvt_pk_bf16_f32 v3, v4, v5
	ds_write_b64 v151, v[2:3]
	s_waitcnt vmcnt(5)
	v_mov_b32_e32 v6, s81
	v_cndmask_b32_e64 v6, v226, v6, s[14:15]
	v_cndmask_b32_e64 v226, v6, v226, s[16:17]
	v_cndmask_b32_e64 v227, 0, v227, s[16:17]
	v_cndmask_b32_e64 v228, v228, 0, s[18:19]
	v_cndmask_b32_e64 v229, v229, 0, s[20:21]
	v_cvt_pk_bf16_f32 v226, v226, v227
	v_cvt_pk_bf16_f32 v227, v228, v229
	ds_write_b64 v152, v[226:227]
	s_waitcnt vmcnt(4)
	v_mov_b32_e32 v6, s81
	v_cndmask_b32_e64 v6, v230, v6, s[22:23]
	v_cndmask_b32_e64 v230, v6, v230, s[24:25]
	v_cndmask_b32_e64 v231, 0, v231, s[24:25]
	v_cndmask_b32_e64 v232, v232, 0, s[26:27]
	v_cndmask_b32_e64 v233, v233, 0, s[28:29]
	v_cvt_pk_bf16_f32 v230, v230, v231
	v_cvt_pk_bf16_f32 v231, v232, v233
	ds_write_b64 v151, v[230:231] offset:8704
	s_waitcnt vmcnt(3)
	v_mov_b32_e32 v6, s81
	v_cndmask_b32_e64 v6, v234, v6, s[30:31]
	v_cndmask_b32_e64 v234, v6, v234, s[34:35]
	v_cndmask_b32_e64 v235, 0, v235, s[34:35]
	v_cndmask_b32_e64 v236, v236, 0, s[36:37]
	v_cndmask_b32_e64 v237, v237, 0, s[38:39]
	v_cvt_pk_bf16_f32 v234, v234, v235
	v_cvt_pk_bf16_f32 v235, v236, v237
	ds_write_b64 v153, v[234:235]
	s_waitcnt vmcnt(2)
	v_mov_b32_e32 v6, s81
	v_cndmask_b32_e64 v6, v238, v6, s[40:41]
	v_cndmask_b32_e64 v238, v6, v238, s[42:43]
	v_cndmask_b32_e64 v239, 0, v239, s[42:43]
	v_cndmask_b32_e64 v240, v240, 0, s[44:45]
	v_cndmask_b32_e64 v241, v241, 0, s[46:47]
	v_cvt_pk_bf16_f32 v238, v238, v239
	v_cvt_pk_bf16_f32 v239, v240, v241
	ds_write_b64 v151, v[238:239] offset:17408
	s_waitcnt vmcnt(1)
	v_mov_b32_e32 v6, s81
	v_cndmask_b32_e64 v6, v242, v6, s[48:49]
	v_cndmask_b32_e64 v242, v6, v242, s[50:51]
	v_cndmask_b32_e64 v243, 0, v243, s[50:51]
	v_cndmask_b32_e64 v244, v244, 0, s[52:53]
	v_cndmask_b32_e64 v245, v245, 0, s[54:55]
	v_cvt_pk_bf16_f32 v242, v242, v243
	v_cvt_pk_bf16_f32 v243, v244, v245
	ds_write_b64 v154, v[242:243]
	s_waitcnt vmcnt(0)
	v_mov_b32_e32 v6, s81
	v_cndmask_b32_e64 v6, v246, v6, s[56:57]
	v_cndmask_b32_e64 v246, v6, v246, s[58:59]
	v_cndmask_b32_e64 v247, 0, v247, s[58:59]
	v_cndmask_b32_e64 v248, v248, 0, s[60:61]
	v_cndmask_b32_e64 v249, v249, 0, s[62:63]
	v_cvt_pk_bf16_f32 v246, v246, v247
	v_cvt_pk_bf16_f32 v247, v248, v249
	ds_write_b64 v151, v[246:247] offset:26112
	global_load_dwordx4 v[0:3], v[0:1], off
	v_mov_b32_e32 v4, s81
	s_waitcnt vmcnt(0)
	v_cndmask_b32_e64 v4, v0, v4, s[64:65]
	v_cndmask_b32_e64 v0, v4, v0, s[66:67]
	v_cndmask_b32_e64 v1, 0, v1, s[66:67]
	v_cndmask_b32_e64 v2, v2, 0, s[68:69]
	v_cndmask_b32_e64 v3, v3, 0, s[70:71]
	v_cvt_pk_bf16_f32 v0, v0, v1
	v_cvt_pk_bf16_f32 v1, v2, v3
	ds_write_b64 v155, v[0:1]
	v_lshlrev_b32_e32 v0, 2, v56
	v_lshl_or_b32 v12, s0, 10, v0
	global_load_dwordx4 v[4:7], v12, s[76:77] offset:16
	global_load_dwordx4 v[0:3], v12, s[76:77]
	global_load_dwordx4 v[8:11], v12, s[78:79] offset:16
	s_nop 0
	global_load_dwordx4 v[12:15], v12, s[78:79]
	s_nop 0
	global_load_dword v84, v16, s[82:83]
	global_load_dword v86, v16, s[82:83] offset:64
	global_load_dword v88, v16, s[82:83] offset:128
	global_load_dword v90, v16, s[82:83] offset:192
